# stacked: attention K loads via scalar base, unit-start loads in flight together, oddnorm and in-proj epilogue load hoists (all bit-identical work/round-trip removals)
# speedup vs baseline: 1.0120x; 1.0112x over previous
; #define GAS __attribute__((address_space(1)))
; #define GAS __attribute__((address_space(1)))
; template <int VAR> DI void phase_attn(LAS unsigned char* lds, const bf16_t* Q, const bf16_t* K, const bf16_t* VT, bf16_t* O) {
;     ...
;         { const bf16_t* qp = Q + (rowb + tq) * 1536 + h * 96 + 8 * hi;
; #pragma unroll
;           for (int s = 0; s < 6; ++s) qr[s] = *(GAS const bf16x8*)(qp + 16 * s); }
;         const bf16_t* Kh = K + (size_t)bh * TT * 96; const bf16_t* Vh = VT + (size_t)(bh * 64 + vd) * 4160;
;         u32x4 kr0, kr1 = {0u, 0u, 0u, 0u}, vr;
.LBB0_42:
	s_lshl_b32 s41, s8, 8
	s_add_i32 s36, s41, s17
	v_or_b32_e32 v201, s36, v134
	v_min_i32_e32 v0, 0x100f, v201
	s_ashr_i32 s37, s40, 4
	v_ashrrev_i32_e32 v1, 31, v0
	v_mov_b32_e32 v2, 0x1010
	v_mad_i64_i32 v[0:1], s[0:1], s37, v2, v[0:1]
	v_mov_b64_e32 v[2:3], s[28:29]
	s_and_b32 s19, s40, 15
	v_mad_u64_u32 v[2:3], s[0:1], v0, s84, v[2:3]
	v_mad_i32_i24 v3, v1, s84, v3
	s_mul_i32 s98, s19, 0xc0
	v_lshl_add_u64 v[0:1], v[2:3], 0, s[98:99]
	v_lshl_add_u64 v[0:1], v[0:1], 0, v[64:65]
	s_mul_i32 s1, s40, 0xc0c00
	v_mov_b32_e32 v94, v65
	v_mov_b32_e32 v95, v65
	v_mov_b32_e32 v96, v65
	v_mov_b32_e32 v97, v65
	global_load_dwordx4 v[66:69], v[0:1], off
	global_load_dwordx4 v[70:73], v[0:1], off offset:32
	global_load_dwordx4 v[74:77], v[0:1], off offset:64
	global_load_dwordx4 v[78:81], v[0:1], off offset:96
	global_load_dwordx4 v[82:85], v[0:1], off offset:128
	global_load_dwordx4 v[86:89], v[0:1], off offset:160
	s_mul_hi_i32 s0, s40, 0xc0c00
	s_add_u32 s8, s10, s1
	s_addc_u32 s9, s11, s0
	s_mov_b64 s[100:101], s[8:9]
	v_lshl_add_u64 v[0:1], s[8:9], 0, v[136:137]
	v_lshl_add_u64 v[0:1], v[138:139], 1, v[0:1]
	global_load_dwordx4 v[90:93], v[0:1], off
	s_and_saveexec_b64 s[0:1], s[6:7]
	s_cbranch_execz .LBB0_44
	v_lshl_add_u64 v[0:1], s[8:9], 0, v[140:141]
	v_lshl_add_u64 v[0:1], v[142:143], 1, v[0:1]
	global_load_dwordx4 v[94:97], v[0:1], off

.LBB0_64:
	s_add_i32 s42, s42, 1
	s_cmp_lt_i32 s42, s59
	s_cselect_b64 s[0:1], -1, 0
	s_cmp_ge_i32 s42, s59
	s_cbranch_scc1 .LBB0_69
	s_mul_i32 s9, s98, 0xc0
	v_lshlrev_b32_e32 v32, 4, v157
	s_add_u32 vcc_lo, s100, s9
	s_addc_u32 vcc_hi, s101, 0
	global_load_dwordx4 v[90:93], v32, vcc
	s_add_u32 vcc_lo, vcc_lo, 0x2000
	s_addc_u32 vcc_hi, vcc_hi, 0
	s_and_saveexec_b64 s[8:9], s[6:7]
	s_cbranch_execz .LBB0_67
	global_load_dwordx4 v[94:97], v32, vcc

; DI float half_max(float v) { auto rr = __builtin_amdgcn_permlane32_swap(__float_as_uint(v), __float_as_uint(v), false, false); return fmaxf(__uint_as_float(rr[0]), __uint_as_float(rr[1])); }
; template <int VAR> DI void phase_attn(LAS unsigned char* lds, const bf16_t* Q, const bf16_t* K, const bf16_t* VT, bf16_t* O) {
;     ...
;                 float mx;
;                 { float a_ = __builtin_fmaxf(__builtin_fmaxf(p0[0], p0[1]), p1[0]), b_ = __builtin_fmaxf(__builtin_fmaxf(p0[2], p0[3]), p1[1]); a_ = __builtin_fmaxf(__builtin_fmaxf(a_, p1[2]), p1[3]);
; #pragma unroll
;                   for (int r = 4; r < 16; r += 4) { a_ = __builtin_fmaxf(__builtin_fmaxf(a_, p0[r]), p0[r + 1]); b_ = __builtin_fmaxf(__builtin_fmaxf(b_, p0[r + 2]), p0[r + 3]);
;                       a_ = __builtin_fmaxf(__builtin_fmaxf(a_, p1[r]), p1[r + 1]); b_ = __builtin_fmaxf(__builtin_fmaxf(b_, p1[r + 2]), p1[r + 3]); }
;                   mx = half_max(__builtin_fmaxf(a_, b_)); }
;                 if (j == 0) {
;                     mrun = mx;
; #pragma unroll
;                     for (int r = 0; r < 16; ++r) { p0[r] -= mx; p1[r] -= mx; }
;                 } else if (__any(mx > 0.f)) {
;                     const float dl = __builtin_fmaxf(mx, 0.f); mrun += dl; const float fsc = __builtin_amdgcn_exp2f(-dl); lrun *= fsc;
; #pragma unroll
;                     for (int r = 0; r < 16; ++r) { p0[r] -= dl; p1[r] -= dl; o0[r] *= fsc; o1[r] *= fsc; }
;                 }
.LBB0_72:
	s_nop 8
	v_max_f32_e32 v172, v48, v49
	v_max3_f32 v173, v50, v51, v33
	v_max3_f32 v172, v172, v32, v34
	v_max3_f32 v172, v172, v35, v52
	v_max3_f32 v173, v173, v54, v55
	v_max3_f32 v172, v172, v53, v36
	v_max3_f32 v173, v173, v38, v39
	v_max3_f32 v172, v172, v37, v56
	v_max3_f32 v173, v173, v58, v59
	v_max3_f32 v172, v172, v57, v40
	v_max3_f32 v173, v173, v42, v43
	v_max3_f32 v172, v172, v41, v60
	v_max3_f32 v173, v173, v62, v63
	v_max3_f32 v172, v172, v61, v44
	v_max3_f32 v173, v173, v46, v47
	v_max3_f32 v172, v172, v45, v173
	v_mov_b32_e32 v173, v172
	s_nop 1
	v_permlane32_swap_b32_e32 v172, v173
	v_max_f32_e32 v208, v172, v173
	v_cmp_lt_f32_e32 vcc, 4.0, v208
	s_cbranch_vccz .LBB0_74
	v_max_f32_e32 v172, v208, v208
	v_max_f32_e32 v172, 0, v172
	v_exp_f32_e64 v174, -v172
	v_pk_add_f32 v[48:49], v[48:49], v[172:173] op_sel_hi:[1,0] neg_lo:[0,1] neg_hi:[0,1]
	v_pk_add_f32 v[32:33], v[32:33], v[172:173] op_sel_hi:[1,0] neg_lo:[0,1] neg_hi:[0,1]
	v_pk_add_f32 v[50:51], v[50:51], v[172:173] op_sel_hi:[1,0] neg_lo:[0,1] neg_hi:[0,1]
	v_pk_add_f32 v[34:35], v[34:35], v[172:173] op_sel_hi:[1,0] neg_lo:[0,1] neg_hi:[0,1]
	v_pk_add_f32 v[52:53], v[52:53], v[172:173] op_sel_hi:[1,0] neg_lo:[0,1] neg_hi:[0,1]
	v_pk_add_f32 v[36:37], v[36:37], v[172:173] op_sel_hi:[1,0] neg_lo:[0,1] neg_hi:[0,1]
	v_pk_add_f32 v[54:55], v[54:55], v[172:173] op_sel_hi:[1,0] neg_lo:[0,1] neg_hi:[0,1]
	v_pk_add_f32 v[38:39], v[38:39], v[172:173] op_sel_hi:[1,0] neg_lo:[0,1] neg_hi:[0,1]
	v_pk_add_f32 v[56:57], v[56:57], v[172:173] op_sel_hi:[1,0] neg_lo:[0,1] neg_hi:[0,1]
	v_pk_add_f32 v[40:41], v[40:41], v[172:173] op_sel_hi:[1,0] neg_lo:[0,1] neg_hi:[0,1]
	v_pk_add_f32 v[58:59], v[58:59], v[172:173] op_sel_hi:[1,0] neg_lo:[0,1] neg_hi:[0,1]
	v_pk_add_f32 v[42:43], v[42:43], v[172:173] op_sel_hi:[1,0] neg_lo:[0,1] neg_hi:[0,1]
	v_pk_add_f32 v[60:61], v[60:61], v[172:173] op_sel_hi:[1,0] neg_lo:[0,1] neg_hi:[0,1]
	v_pk_add_f32 v[44:45], v[44:45], v[172:173] op_sel_hi:[1,0] neg_lo:[0,1] neg_hi:[0,1]
	v_pk_add_f32 v[62:63], v[62:63], v[172:173] op_sel_hi:[1,0] neg_lo:[0,1] neg_hi:[0,1]
	v_pk_add_f32 v[46:47], v[46:47], v[172:173] op_sel_hi:[1,0] neg_lo:[0,1] neg_hi:[0,1]
	v_pk_mul_f32 v[14:15], v[14:15], v[174:175] op_sel_hi:[1,0]
	v_pk_mul_f32 v[12:13], v[12:13], v[174:175] op_sel_hi:[1,0]
	v_pk_mul_f32 v[10:11], v[10:11], v[174:175] op_sel_hi:[1,0]
	v_pk_mul_f32 v[8:9], v[8:9], v[174:175] op_sel_hi:[1,0]
	v_pk_mul_f32 v[6:7], v[6:7], v[174:175] op_sel_hi:[1,0]
	v_pk_mul_f32 v[4:5], v[4:5], v[174:175] op_sel_hi:[1,0]
	v_pk_mul_f32 v[2:3], v[2:3], v[174:175] op_sel_hi:[1,0]
	v_pk_mul_f32 v[0:1], v[0:1], v[174:175] op_sel_hi:[1,0]
	v_pk_mul_f32 v[30:31], v[30:31], v[174:175] op_sel_hi:[1,0]
	v_pk_mul_f32 v[28:29], v[28:29], v[174:175] op_sel_hi:[1,0]
	v_pk_mul_f32 v[26:27], v[26:27], v[174:175] op_sel_hi:[1,0]
	v_pk_mul_f32 v[24:25], v[24:25], v[174:175] op_sel_hi:[1,0]
	v_pk_mul_f32 v[22:23], v[22:23], v[174:175] op_sel_hi:[1,0]
	v_pk_mul_f32 v[20:21], v[20:21], v[174:175] op_sel_hi:[1,0]
	v_pk_mul_f32 v[18:19], v[18:19], v[174:175] op_sel_hi:[1,0]
	v_pk_mul_f32 v[16:17], v[16:17], v[174:175] op_sel_hi:[1,0]
	v_add_f32_e32 v202, v202, v172
	v_mul_f32_e32 v203, v203, v174

; #define GAS __attribute__((address_space(1)))
; #define GAS __attribute__((address_space(1)))
; DI int otid() { int t = threadIdx.x; asm volatile("" : "+v"(t)); return t; }
; DI int obid() { int b = blockIdx.x; asm volatile("" : "+s"(b)); return b; }
; DI void phase_oddnorm(const bf16_t* U2, const float* qn, const float* kvn, const float* cs, const float* sn, bf16_t* CQN, bf16_t* CKVN, bf16_t* K) {
;     const int lane = otid() & 63, gw = obid() * 8 + (otid() >> 6), nw = gridDim.x * 8;
;     float gq[6], gk[4];
; #pragma unroll
;     for (int e = 0; e < 6; ++e) gq[e] = qn[lane * 6 + e];
; #pragma unroll
;     for (int e = 0; e < 4; ++e) gk[e] = kvn[lane * 4 + e];
;     for (int row = gw; row < M; row += nw) {
;         const bf16_t* u = U2 + (size_t)row * 768; const int t = row % TT;
;         GAS const unsigned* uq = (GAS const unsigned*)(u + lane * 6); const unsigned w0 = uq[0], w1 = uq[1], w2 = uq[2];
.LBB0_95:
	s_andn2_b64 vcc, exec, s[0:1]
	s_mov_b64 s[0:1], 0
	s_cbranch_vccnz .LBB0_102
	v_mov_b32_e32 v9, v157
	s_mov_b32 s4, s65
	v_mov_b32_e32 v0, v157
	s_nop 0
	v_ashrrev_i32_e32 v0, 6, v0
	v_lshl_add_u32 v8, s4, 3, v0
	v_cmp_gt_i32_e32 vcc, s64, v8
	s_and_saveexec_b64 s[4:5], vcc
	s_cbranch_execz .LBB0_103
	s_load_dwordx4 s[12:15], s[92:93], 0x78
	s_mul_i32 s6, s33, 0x600
	v_and_b32_e32 v16, 63, v9
	v_mul_u32_u24_e32 v18, 6, v16
	v_lshlrev_b32_e32 v0, 2, v18
	s_waitcnt lgkmcnt(0)
	s_add_u32 s6, s12, s6
	s_addc_u32 s7, s13, 0
	s_lshl_b32 s8, s33, 10
	s_add_u32 s8, s14, s8
	s_addc_u32 s9, s15, 0
	v_lshlrev_b32_e32 v4, 4, v16
	global_load_dwordx2 v[10:11], v0, s[6:7] offset:16
	s_nop 0
	global_load_dwordx4 v[0:3], v0, s[6:7]
	v_readlane_b32 s6, v254, 18
	global_load_dwordx4 v[4:7], v4, s[8:9]
	v_lshlrev_b32_e32 v64, 1, v18
	v_readlane_b32 s7, v254, 19
	v_lshlrev_b32_e32 v20, 2, v16
	v_and_b32_e32 v24, 31, v9
	v_lshl_add_u64 v[12:13], s[6:7], 0, v[64:65]
	v_lshlrev_b32_e32 v64, 3, v16
	v_lshl_add_u64 v[14:15], s[34:35], 0, v[64:65]
	v_and_b32_e32 v19, 15, v9
	v_and_b32_e32 v9, 16, v9
	v_lshlrev_b32_e32 v64, 1, v16
	v_cmp_eq_u32_e64 s[6:7], 0, v9
	v_cmp_gt_u32_e64 s[8:9], 32, v16
	v_lshl_add_u64 v[16:17], s[10:11], 0, v[64:65]
	v_lshl_or_b32 v22, v8, 4, v19
	s_lshl_b32 s14, s58, 4
	s_mov_b64 s[18:19], 0
	v_lshlrev_b32_e32 v64, 1, v18
	v_lshlrev_b32_e32 v18, 1, v20
	v_lshlrev_b32_e32 v20, 1, v24
	v_mov_b32_e32 v58, v18
	v_mov_b32_e32 v59, v65
	v_mov_b32_e32 v60, v20
	v_mov_b32_e32 v61, v65
	s_branch .LBB0_99

; #define GAS __attribute__((address_space(1)))
; __device__ __forceinline__ unsigned pk2(float lo, float hi) { f32x2v v = {lo, hi}; bf16x2v b = __builtin_convertvector(v, bf16x2v); return __builtin_bit_cast(unsigned, b); }
; #define GAS __attribute__((address_space(1)))
; DI float bflo(unsigned w) { return __uint_as_float(w << 16); }
; DI float bfhi(unsigned w) { return __uint_as_float(w & 0xffff0000u); }
; DI float wave_sum(float v) { v += swz_xor<1>(v); v += swz_xor<2>(v); v += swz_xor<4>(v); v += swz_xor<8>(v); v += swz_xor<16>(v); return half_sum(v); }
; DI void phase_oddnorm(const bf16_t* U2, const float* qn, const float* kvn, const float* cs, const float* sn, bf16_t* CQN, bf16_t* CKVN, bf16_t* K) {
;     ...
;         const bf16_t* u = U2 + (size_t)row * 768; const int t = row % TT;
;         GAS const unsigned* uq = (GAS const unsigned*)(u + lane * 6); const unsigned w0 = uq[0], w1 = uq[1], w2 = uq[2];
;         float q[6] = {bflo(w0), bfhi(w0), bflo(w1), bfhi(w1), bflo(w2), bfhi(w2)};
;         float ss = 0.f;
; #pragma unroll
;         for (int e = 0; e < 6; ++e) ss += q[e] * q[e];
;         const float rq = rsqrtf(wave_sum(ss) * (1.f / 384) + EPS);
;         GAS unsigned* oq = (GAS unsigned*)(CQN + (size_t)row * 384 + lane * 6);
;         oq[0] = pk2(q[0] * rq * gq[0], q[1] * rq * gq[1]); oq[1] = pk2(q[2] * rq * gq[2], q[3] * rq * gq[3]); oq[2] = pk2(q[4] * rq * gq[4], q[5] * rq * gq[5]);
;         const u32x2 kw = *(GAS const u32x2*)(u + 384 + lane * 4);
;         float kv[4] = {bflo(kw.x), bfhi(kw.x), bflo(kw.y), bfhi(kw.y)};
;         float s2 = (kv[0] * kv[0] + kv[1] * kv[1]) + (kv[2] * kv[2] + kv[3] * kv[3]);
;         const float rk = rsqrtf(wave_sum(s2) * (1.f / 256) + EPS);
;         u32x2 ow; ow.x = pk2(kv[0] * rk * gk[0], kv[1] * rk * gk[1]); ow.y = pk2(kv[2] * rk * gk[2], kv[3] * rk * gk[3]);
;         *(GAS u32x2*)(CKVN + (size_t)row * 256 + lane * 4) = ow;
.LBB0_99:
	v_mov_b64_e32 v[24:25], s[38:39]
	s_movk_i32 s10, 0x600
	v_mad_i64_i32 v[28:29], s[10:11], v8, s10, v[24:25]
	v_lshl_add_u64 v[24:25], v[28:29], 0, v[64:65]
	global_load_dwordx3 v[24:26], v[24:25], off
	v_lshl_add_u64 v[54:55], v[28:29], 0, v[58:59]
	global_load_dwordx2 v[54:55], v[54:55], off offset:768
	v_lshl_add_u64 v[56:57], v[28:29], 0, v[60:61]
	global_load_ushort v56, v[56:57], off offset:1280
	s_waitcnt vmcnt(0)
	v_lshlrev_b32_e32 v30, 16, v24
	v_and_b32_e32 v31, 0xffff0000, v24
	v_lshlrev_b32_e32 v24, 16, v25
	v_and_b32_e32 v25, 0xffff0000, v25
	v_lshlrev_b32_e32 v32, 16, v26
	v_and_b32_e32 v33, 0xffff0000, v26
	v_pk_mul_f32 v[26:27], v[30:31], v[30:31]
	v_pk_mul_f32 v[34:35], v[24:25], v[24:25]
	v_add_f32_e32 v9, v26, v27
	v_add_f32_e32 v9, v9, v34
	v_pk_mul_f32 v[36:37], v[32:33], v[32:33]
	v_add_f32_e32 v9, v35, v9
	v_add_f32_e32 v9, v36, v9
	v_add_f32_e32 v9, v37, v9
	s_waitcnt lgkmcnt(0)
	ds_swizzle_b32 v19, v9 offset:swizzle(SWAP,1)
	v_mad_i64_i32 v[34:35], s[10:11], v8, s66, v[12:13]
	s_waitcnt lgkmcnt(0)
	v_add_f32_e32 v9, v9, v19
	ds_swizzle_b32 v19, v9 offset:swizzle(SWAP,2)
	s_waitcnt lgkmcnt(0)
	v_add_f32_e32 v9, v9, v19
	ds_swizzle_b32 v19, v9 offset:swizzle(SWAP,4)
	s_waitcnt lgkmcnt(0)
	v_add_f32_e32 v9, v9, v19
	ds_swizzle_b32 v19, v9 offset:swizzle(SWAP,8)
	s_waitcnt lgkmcnt(0)
	v_add_f32_e32 v9, v9, v19
	ds_swizzle_b32 v19, v9 offset:swizzle(SWAP,16)
	s_waitcnt lgkmcnt(0)
	v_add_f32_e32 v9, v9, v19
	v_mov_b32_e32 v19, v9
	s_nop 1
	v_permlane32_swap_b32_e32 v9, v19
	v_add_f32_e32 v9, v9, v19
	v_fmamk_f32 v9, v9, 0x3b2aaaab, v156
	v_mul_f32_e32 v19, 0x4b800000, v9
	v_cmp_gt_f32_e32 vcc, s90, v9
	s_nop 1
	v_cndmask_b32_e32 v9, v9, v19, vcc
	v_rsq_f32_e32 v9, v9
	v_mov_b32_e32 v19, v65
	v_lshl_add_u64 v[36:37], v[28:29], 0, v[18:19]
	v_mul_f32_e32 v19, 0x45800000, v9
	v_cndmask_b32_e32 v26, v9, v19, vcc
	v_pk_mul_f32 v[30:31], v[26:27], v[30:31] op_sel_hi:[0,1]
	v_pk_mul_f32 v[24:25], v[26:27], v[24:25] op_sel_hi:[0,1]
	v_pk_mul_f32 v[26:27], v[26:27], v[32:33] op_sel_hi:[0,1]
	v_pk_mul_f32 v[30:31], v[0:1], v[30:31]
	v_pk_mul_f32 v[32:33], v[2:3], v[24:25]
	v_pk_mul_f32 v[26:27], v[10:11], v[26:27]
	v_cvt_pk_bf16_f32 v24, v30, v31
	v_cvt_pk_bf16_f32 v25, v32, v33
	v_cvt_pk_bf16_f32 v26, v26, v27
	global_store_dwordx3 v[34:35], v[24:26], off
	s_nop 1
	v_mov_b32_e32 v24, v54
	v_mov_b32_e32 v25, v55
	v_and_b32_e32 v27, 0xffff0000, v25
	v_lshlrev_b32_e32 v26, 16, v25
	v_lshlrev_b32_e32 v30, 16, v24
	v_and_b32_e32 v31, 0xffff0000, v24
	v_pk_mul_f32 v[24:25], v[26:27], v[26:27]
	v_pk_mul_f32 v[32:33], v[30:31], v[30:31]
	v_add_f32_e32 v9, v24, v25
	v_add_f32_e32 v19, v32, v33
	v_add_f32_e32 v9, v19, v9
	ds_swizzle_b32 v19, v9 offset:swizzle(SWAP,1)
	s_waitcnt lgkmcnt(0)
	v_add_f32_e32 v9, v9, v19
	ds_swizzle_b32 v19, v9 offset:swizzle(SWAP,2)
	s_waitcnt lgkmcnt(0)
	v_add_f32_e32 v9, v9, v19
	ds_swizzle_b32 v19, v9 offset:swizzle(SWAP,4)
	s_waitcnt lgkmcnt(0)
	v_add_f32_e32 v9, v9, v19
	ds_swizzle_b32 v19, v9 offset:swizzle(SWAP,8)
	s_waitcnt lgkmcnt(0)
	v_add_f32_e32 v19, v9, v19
	ds_swizzle_b32 v21, v19 offset:swizzle(SWAP,16)
	v_ashrrev_i32_e32 v9, 31, v8
	v_lshlrev_b64 v[24:25], 9, v[8:9]
	v_lshl_add_u64 v[24:25], v[14:15], 0, v[24:25]
	s_waitcnt lgkmcnt(0)
	v_add_f32_e32 v19, v19, v21
	v_mov_b32_e32 v21, v19
	s_nop 1
	v_permlane32_swap_b32_e32 v19, v21
	v_add_f32_e32 v19, v19, v21
	v_fmamk_f32 v19, v19, 0x3b800000, v156
	v_mul_f32_e32 v21, 0x4b800000, v19
	v_cmp_gt_f32_e32 vcc, s90, v19
	s_nop 1
	v_cndmask_b32_e32 v19, v19, v21, vcc
	v_rsq_f32_e32 v19, v19
	v_mov_b32_e32 v21, v65
	v_mul_f32_e32 v9, 0x45800000, v19
	v_cndmask_b32_e32 v32, v19, v9, vcc
	v_pk_mul_f32 v[30:31], v[32:33], v[30:31] op_sel_hi:[0,1]
	v_pk_mul_f32 v[26:27], v[32:33], v[26:27] op_sel_hi:[0,1]
	v_pk_mul_f32 v[30:31], v[4:5], v[30:31]
	v_pk_mul_f32 v[26:27], v[6:7], v[26:27]
	v_cvt_pk_bf16_f32 v30, v30, v31
	v_cvt_pk_bf16_f32 v31, v26, v27
	global_store_dwordx2 v[24:25], v[30:31], off
	v_mov_b32_e32 v9, v56
	v_lshlrev_b32_e32 v9, 16, v9
	ds_swizzle_b32 v19, v9 offset:swizzle(SWAP,16)
	s_and_saveexec_b64 s[34:35], s[8:9]
	s_cbranch_execz .LBB0_98
; template <int MASK> DI float swz_xor(float v) { return __int_as_float(__builtin_amdgcn_ds_swizzle(__float_as_int(v), (MASK << 10) | 0x1f)); }
; DI float bf1(const bf16_t* p) { return __uint_as_float((unsigned)(*(GAS const bf16_t*)p) << 16); }
; DI bf16_t tobf(float f) { return (bf16_t)(pk2(f, 0.f) & 0xffffu); }
; DI void phase_oddnorm(const bf16_t* U2, const float* qn, const float* kvn, const float* cs, const float* sn, bf16_t* CQN, bf16_t* CKVN, bf16_t* K) {
;     ...
;         const float x = bf1(u + 640 + (lane & 31)); const float xp = swz_xor<16>(x);
;         const float c = cs[t * 16 + (lane & 15)], s = sn[t * 16 + (lane & 15)];
;         const float o = (lane & 16) ? (x * c + xp * s) : (x * c - xp * s);
;         const bf16_t ob = tobf(o);
;         if (lane < 32) {
;             const int b_ = row / TT; bf16_t* kp = K + ((size_t)(b_ * 16) * TT + t) * 96 + 64 + lane;
; #pragma unroll
;             for (int h = 0; h < 16; ++h) kp[(size_t)h * TT * 96] = ob;
;         }
	v_mul_hi_i32 v21, v8, s85
	v_lshrrev_b32_e32 v23, 31, v21
	v_ashrrev_i32_e32 v21, 11, v21
	v_add_u32_e32 v21, v21, v23
	v_mul_i32_i24_e32 v23, 0x1010, v21
	v_lshlrev_b32_e32 v24, 4, v23
	v_sub_u32_e32 v24, v22, v24
	v_ashrrev_i32_e32 v25, 31, v24
	v_readlane_b32 s10, v254, 26
	v_lshlrev_b64 v[24:25], 2, v[24:25]
	v_readlane_b32 s11, v254, 27
	v_lshlrev_b32_e32 v21, 4, v21
	s_mov_b32 s12, 0x787000
	v_lshl_add_u64 v[26:27], s[10:11], 0, v[24:25]
	v_readlane_b32 s10, v254, 24
	flat_load_dword v52, v[26:27]
	v_readlane_b32 s11, v254, 25
	s_nop 1
	v_lshl_add_u64 v[24:25], s[10:11], 0, v[24:25]
	flat_load_dword v53, v[24:25]
	v_sub_u32_e32 v24, v8, v23
	v_mul_hi_i32_i24_e32 v27, 0x1010, v21
	v_mul_i32_i24_e32 v26, 0x1010, v21
	v_ashrrev_i32_e32 v25, 31, v24
	v_lshl_add_u64 v[24:25], v[26:27], 0, v[24:25]
	v_mad_u64_u32 v[26:27], s[10:11], v24, s71, v[16:17]
	v_mov_b32_e32 v24, v27
	s_mov_b32 s10, 0x6c6000
	v_add_co_u32_e32 v28, vcc, s10, v26
	v_mad_u64_u32 v[24:25], s[10:11], v25, s71, v[24:25]
	s_mov_b64 s[10:11], vcc
	v_add_co_u32_e32 v30, vcc, s12, v26
	s_mov_b32 s12, 0xc0000
	v_add_co_u32_e64 v32, s[12:13], s12, v26
	v_addc_co_u32_e64 v29, s[10:11], 0, v24, s[10:11]
	s_nop 0
	v_addc_co_u32_e64 v33, s[12:13], 0, v24, s[12:13]
	s_mov_b32 s12, 0x181000
	s_nop 0
	v_add_co_u32_e64 v34, s[12:13], s12, v26
	v_addc_co_u32_e32 v31, vcc, 0, v24, vcc
	s_nop 0
	v_addc_co_u32_e64 v35, s[12:13], 0, v24, s[12:13]
	s_mov_b32 s12, 0x242000
	s_nop 0
	v_add_co_u32_e64 v36, s[12:13], s12, v26
	s_mov_b32 s10, 0x848000
	s_nop 0
	v_addc_co_u32_e64 v37, s[12:13], 0, v24, s[12:13]
	s_mov_b32 s12, 0x303000
	s_nop 0
	v_add_co_u32_e64 v38, s[12:13], s12, v26
	v_add_co_u32_e32 v48, vcc, s10, v26
	s_nop 0
	v_addc_co_u32_e64 v39, s[12:13], 0, v24, s[12:13]
	s_mov_b32 s12, 0x3c3000
	s_nop 0
	v_add_co_u32_e64 v40, s[12:13], s12, v26
	v_addc_co_u32_e32 v49, vcc, 0, v24, vcc
	s_nop 0
	v_addc_co_u32_e64 v41, s[12:13], 0, v24, s[12:13]
	s_mov_b32 s12, 0x484000
	s_nop 0
	v_add_co_u32_e64 v42, s[12:13], s12, v26
	v_add_co_u32_e32 v50, vcc, 0x909000, v26
	s_nop 0
	v_addc_co_u32_e64 v43, s[12:13], 0, v24, s[12:13]
	s_mov_b32 s12, 0x545000
	s_nop 0
	v_add_co_u32_e64 v44, s[12:13], s12, v26
	v_mov_b32_e32 v27, v24
	s_nop 0
	v_addc_co_u32_e64 v45, s[12:13], 0, v24, s[12:13]
	s_mov_b32 s12, 0x606000
	s_nop 0
	v_add_co_u32_e64 v46, s[12:13], s12, v26
	v_addc_co_u32_e32 v51, vcc, 0, v24, vcc
	s_nop 0
	v_addc_co_u32_e64 v47, s[12:13], 0, v24, s[12:13]
	s_waitcnt vmcnt(0) lgkmcnt(0)
	v_mul_f32_e32 v19, v52, v19
	v_cndmask_b32_e64 v19, v19, -v19, s[6:7]
	v_fmac_f32_e32 v19, v53, v9
	v_cvt_pk_bf16_f32 v9, v19, s0
	flat_store_short v[26:27], v9 offset:128
	flat_store_short v[32:33], v9 offset:3200
	flat_store_short v[34:35], v9 offset:2176
	flat_store_short v[36:37], v9 offset:1152
	flat_store_short v[38:39], v9 offset:128
	flat_store_short v[40:41], v9 offset:3200
	flat_store_short v[42:43], v9 offset:2176
	flat_store_short v[44:45], v9 offset:1152
	flat_store_short v[46:47], v9 offset:128
	flat_store_short v[28:29], v9 offset:3200
	flat_store_short v[30:31], v9 offset:2176
	flat_store_short v[48:49], v9 offset:1152
	flat_store_short v[50:51], v9 offset:128
	v_add_co_u32_e32 v28, vcc, 0x9c9000, v26
	s_nop 1
	v_addc_co_u32_e32 v29, vcc, 0, v24, vcc
	flat_store_short v[28:29], v9 offset:3200
	v_add_co_u32_e32 v28, vcc, 0xa8a000, v26
	s_nop 1
	v_addc_co_u32_e32 v29, vcc, 0, v24, vcc
	v_add_co_u32_e32 v26, vcc, 0xb4b000, v26
	flat_store_short v[28:29], v9 offset:2176
	s_nop 0
	v_addc_co_u32_e32 v27, vcc, 0, v24, vcc
	flat_store_short v[26:27], v9 offset:1152
	s_branch .LBB0_98

; #define GAS __attribute__((address_space(1)))
; __device__ __forceinline__ unsigned pk2(float lo, float hi) { f32x2v v = {lo, hi}; bf16x2v b = __builtin_convertvector(v, bf16x2v); return __builtin_bit_cast(unsigned, b); }
; #define GAS __attribute__((address_space(1)))
; __device__ __forceinline__ float row_rstd(const float* ss, int row, int fq) {
;     const f32x4 a = *(GAS const f32x4*)(ss + (size_t)row * 16 + 4 * fq);
;     float s = (a[0] + a[1]) + (a[2] + a[3]);
;     s += __int_as_float(__builtin_amdgcn_ds_swizzle(__float_as_int(s), (16 << 10) | 0x1f));
;     { auto rr = __builtin_amdgcn_permlane32_swap(__float_as_uint(s), __float_as_uint(s), false, false); s = __uint_as_float(rr[0]) + __uint_as_float(rr[1]); }
;     return rsqrtf(s * (1.f / 1024) + 1e-6f);
; }
;     __device__ __forceinline__ void operator()(const f32x4 (&acc)[2][2][4][2], const Unit& u, int wr, int wc, int fr, int fq) const {
;     ...
;             for (int m = 0; m < 4; ++m) { const int row = row0 + ai * HALF + m * 16; bf16_t* rp = base + (size_t)row * ld;
;                 float rs = 1.f; if (MODE == 0 && ss) rs = row_rstd(ss, row, fq);
; #pragma unroll
;                 for (int bj = 0; bj < 2; ++bj) { int c = c0 + bj * HALF;
;                     if (MODE == 1) { const int b_ = row / TT, t_ = row - b_ * TT; rp = base; c = (((b_ * 16 + (c >> 6)) * TT + t_) * 96) + (c & 63); }
;                     if (MODE == 2) { const int b_ = c / TT, t_ = c - b_ * TT; rp = base + ((size_t)((b_ * 16 + (row >> 6)) * 64 + (row & 63))) * 4160; c = t_; }
;                     const f32x4 v0 = acc[ai][bj][m][0] * rs, v1 = acc[ai][bj][m][1] * rs; u32x4 w; w.x = pk2(v0[0], v0[1]); w.y = pk2(v0[2], v0[3]); w.z = pk2(v1[0], v1[1]); w.w = pk2(v1[2], v1[3]);
;                     *(GAS u32x4*)(rp + c) = w; } }
.LBB0_508:
	s_waitcnt lgkmcnt(0)
	v_lshl_add_u32 v132, s64, 8, v208
	v_cndmask_b32_e64 v66, 0, 1, s[52:53]
	v_ashrrev_i32_e32 v133, 31, v132
	v_mov_b32_e32 v64, 1.0
	v_cmp_ne_u32_e64 s[28:29], 1, v66
	s_andn2_b64 vcc, exec, s[52:53]
	v_mov_b32_e32 v134, 1.0
	s_cbranch_vccnz .LBB0_510
	v_mad_u64_u32 v[204:205], vcc, v132, 64, v[174:175]
	global_load_dwordx4 v[184:187], v[204:205], off
	v_add_u32_e32 v232, 16, v132
	v_mad_u64_u32 v[204:205], vcc, v232, 64, v[174:175]
	global_load_dwordx4 v[188:191], v[204:205], off
	v_add_u32_e32 v232, 32, v132
	v_mad_u64_u32 v[204:205], vcc, v232, 64, v[174:175]
	global_load_dwordx4 v[192:195], v[204:205], off
	v_add_u32_e32 v232, 48, v132
	v_mad_u64_u32 v[204:205], vcc, v232, 64, v[174:175]
	global_load_dwordx4 v[196:199], v[204:205], off
	v_add_u32_e32 v232, 128, v132
	v_mad_u64_u32 v[204:205], vcc, v232, 64, v[174:175]
	global_load_dwordx4 v[200:203], v[204:205], off
	v_add_u32_e32 v232, 144, v132
	v_mad_u64_u32 v[204:205], vcc, v232, 64, v[174:175]
	global_load_dwordx4 v[220:223], v[204:205], off
	v_add_u32_e32 v232, 160, v132
	v_mad_u64_u32 v[204:205], vcc, v232, 64, v[174:175]
	global_load_dwordx4 v[224:227], v[204:205], off
	v_add_u32_e32 v232, 176, v132
	v_mad_u64_u32 v[204:205], vcc, v232, 64, v[174:175]
	global_load_dwordx4 v[228:231], v[204:205], off
	s_waitcnt vmcnt(0)
	v_lshlrev_b64 v[66:67], 6, v[132:133]
	v_lshl_add_u64 v[66:67], v[174:175], 0, v[66:67]
	v_mov_b32_e32 v134, v184
	v_mov_b32_e32 v135, v185
	v_mov_b32_e32 v136, v186
	v_mov_b32_e32 v137, v187
	v_mov_b32_e32 v66, v135
	v_mov_b32_e32 v67, v136
	v_mov_b32_e32 v135, v137
	v_pk_add_f32 v[66:67], v[66:67], v[134:135]
	s_nop 0
	v_add_f32_e32 v66, v66, v67
	ds_swizzle_b32 v67, v66 offset:swizzle(SWAP,16)
	s_waitcnt lgkmcnt(0)
	v_add_f32_e32 v66, v66, v67
	v_mov_b32_e32 v67, v66
	s_nop 1
	v_permlane32_swap_b32_e32 v66, v67
	v_add_f32_e32 v66, v66, v67
	v_fmamk_f32 v66, v66, 0x3a800000, v156
	v_mul_f32_e32 v67, 0x4b800000, v66
	v_cmp_gt_f32_e32 vcc, s90, v66
	s_nop 1
	v_cndmask_b32_e32 v66, v66, v67, vcc
	v_rsq_f32_e32 v66, v66
	s_nop 0
	v_mul_f32_e32 v67, 0x45800000, v66
	v_cndmask_b32_e32 v134, v66, v67, vcc
.LBB0_510:
	s_lshl_b32 s16, s11, 8
	v_readlane_b32 s11, v254, 10
	s_cmp_lt_i32 s16, s11
	s_cselect_b64 s[6:7], -1, 0
	s_and_b64 s[6:7], s[6:7], exec
	s_cselect_b32 s17, 0, s11
	v_readlane_b32 s11, v254, 9
	s_cselect_b32 s11, s15, s11
	v_or_b32_e32 v66, s16, v210
	v_subrev_u32_e32 v66, s17, v66
	v_mad_u64_u32 v[136:137], s[16:17], s11, v132, 0
	v_mov_b32_e32 v138, v137
	v_mad_u64_u32 v[138:139], s[16:17], s11, v133, v[138:139]
	s_cselect_b32 s7, s87, s1
	s_cselect_b32 s6, s86, s0
	v_mov_b32_e32 v137, v138
	v_lshl_add_u64 v[136:137], v[136:137], 1, s[6:7]
	v_pk_mul_f32 v[130:131], v[130:131], v[134:135] op_sel_hi:[1,0]
	v_pk_mul_f32 v[128:129], v[128:129], v[134:135] op_sel_hi:[1,0]
	v_pk_mul_f32 v[138:139], v[126:127], v[134:135] op_sel_hi:[1,0]
	v_pk_mul_f32 v[126:127], v[124:125], v[134:135] op_sel_hi:[1,0]
	v_ashrrev_i32_e32 v67, 31, v66
	v_cvt_pk_bf16_f32 v124, v128, v129
	v_cvt_pk_bf16_f32 v125, v130, v131
	v_cvt_pk_bf16_f32 v126, v126, v127
	v_cvt_pk_bf16_f32 v127, v138, v139
	v_lshl_add_u64 v[128:129], v[66:67], 1, v[136:137]
	global_store_dwordx4 v[128:129], v[124:127], off
	v_pk_mul_f32 v[122:123], v[122:123], v[134:135] op_sel_hi:[1,0]
	v_pk_mul_f32 v[120:121], v[120:121], v[134:135] op_sel_hi:[1,0]
	v_pk_mul_f32 v[124:125], v[118:119], v[134:135] op_sel_hi:[1,0]
	v_pk_mul_f32 v[118:119], v[116:117], v[134:135] op_sel_hi:[1,0]
	v_cvt_pk_bf16_f32 v116, v120, v121
	v_cvt_pk_bf16_f32 v117, v122, v123
	v_cvt_pk_bf16_f32 v118, v118, v119
	v_cvt_pk_bf16_f32 v119, v124, v125
	global_store_dwordx4 v[128:129], v[116:119], off offset:256
	s_and_b64 vcc, exec, s[28:29]
	s_nop 0
	v_or_b32_e32 v116, 16, v132
	v_ashrrev_i32_e32 v117, 31, v116
	s_cbranch_vccnz .LBB0_512
	v_lshlrev_b64 v[118:119], 6, v[116:117]
	v_lshl_add_u64 v[118:119], v[174:175], 0, v[118:119]
	v_mov_b32_e32 v118, v188
	v_mov_b32_e32 v119, v189
	v_mov_b32_e32 v120, v190
	v_mov_b32_e32 v121, v191
	v_mov_b32_e32 v122, v119
	v_mov_b32_e32 v123, v120
	v_mov_b32_e32 v119, v121
	v_pk_add_f32 v[118:119], v[122:123], v[118:119]
	s_nop 0
	v_add_f32_e32 v64, v118, v119
	ds_swizzle_b32 v118, v64 offset:swizzle(SWAP,16)
	s_waitcnt lgkmcnt(0)
	v_add_f32_e32 v64, v64, v118
	v_mov_b32_e32 v118, v64
	s_nop 1
	v_permlane32_swap_b32_e32 v64, v118
	v_add_f32_e32 v64, v64, v118
	v_fmamk_f32 v64, v64, 0x3a800000, v156
	v_mul_f32_e32 v118, 0x4b800000, v64
	v_cmp_gt_f32_e32 vcc, s90, v64
	s_nop 1
	v_cndmask_b32_e32 v64, v64, v118, vcc
	v_rsq_f32_e32 v64, v64
	s_nop 0
	v_mul_f32_e32 v118, 0x45800000, v64
	v_cndmask_b32_e32 v64, v64, v118, vcc
; #define GAS __attribute__((address_space(1)))
; __device__ __forceinline__ unsigned pk2(float lo, float hi) { f32x2v v = {lo, hi}; bf16x2v b = __builtin_convertvector(v, bf16x2v); return __builtin_bit_cast(unsigned, b); }
; #define GAS __attribute__((address_space(1)))
; __device__ __forceinline__ float row_rstd(const float* ss, int row, int fq) {
;     const f32x4 a = *(GAS const f32x4*)(ss + (size_t)row * 16 + 4 * fq);
;     float s = (a[0] + a[1]) + (a[2] + a[3]);
;     s += __int_as_float(__builtin_amdgcn_ds_swizzle(__float_as_int(s), (16 << 10) | 0x1f));
;     { auto rr = __builtin_amdgcn_permlane32_swap(__float_as_uint(s), __float_as_uint(s), false, false); s = __uint_as_float(rr[0]) + __uint_as_float(rr[1]); }
;     return rsqrtf(s * (1.f / 1024) + 1e-6f);
; }
;     __device__ __forceinline__ void operator()(const f32x4 (&acc)[2][2][4][2], const Unit& u, int wr, int wc, int fr, int fq) const {
;     ...
;             for (int m = 0; m < 4; ++m) { const int row = row0 + ai * HALF + m * 16; bf16_t* rp = base + (size_t)row * ld;
;                 float rs = 1.f; if (MODE == 0 && ss) rs = row_rstd(ss, row, fq);
; #pragma unroll
;                 for (int bj = 0; bj < 2; ++bj) { int c = c0 + bj * HALF;
;                     if (MODE == 1) { const int b_ = row / TT, t_ = row - b_ * TT; rp = base; c = (((b_ * 16 + (c >> 6)) * TT + t_) * 96) + (c & 63); }
;                     if (MODE == 2) { const int b_ = c / TT, t_ = c - b_ * TT; rp = base + ((size_t)((b_ * 16 + (row >> 6)) * 64 + (row & 63))) * 4160; c = t_; }
;                     const f32x4 v0 = acc[ai][bj][m][0] * rs, v1 = acc[ai][bj][m][1] * rs; u32x4 w; w.x = pk2(v0[0], v0[1]); w.y = pk2(v0[2], v0[3]); w.z = pk2(v1[0], v1[1]); w.w = pk2(v1[2], v1[3]);
;                     *(GAS u32x4*)(rp + c) = w; } }
.LBB0_512:
	v_mad_u64_u32 v[118:119], s[16:17], v116, s11, 0
	v_mov_b32_e32 v116, v119
	v_mad_u64_u32 v[116:117], s[16:17], v117, s11, v[116:117]
	v_mov_b32_e32 v119, v116
	v_lshl_add_u64 v[116:117], v[118:119], 1, s[6:7]
	v_pk_mul_f32 v[114:115], v[114:115], v[64:65] op_sel_hi:[1,0]
	v_pk_mul_f32 v[112:113], v[112:113], v[64:65] op_sel_hi:[1,0]
	v_pk_mul_f32 v[118:119], v[110:111], v[64:65] op_sel_hi:[1,0]
	v_pk_mul_f32 v[110:111], v[108:109], v[64:65] op_sel_hi:[1,0]
	v_cvt_pk_bf16_f32 v108, v112, v113
	v_cvt_pk_bf16_f32 v109, v114, v115
	v_cvt_pk_bf16_f32 v110, v110, v111
	v_cvt_pk_bf16_f32 v111, v118, v119
	v_lshl_add_u64 v[112:113], v[66:67], 1, v[116:117]
	global_store_dwordx4 v[112:113], v[108:111], off
	v_pk_mul_f32 v[106:107], v[106:107], v[64:65] op_sel_hi:[1,0]
	v_pk_mul_f32 v[104:105], v[104:105], v[64:65] op_sel_hi:[1,0]
	v_pk_mul_f32 v[108:109], v[102:103], v[64:65] op_sel_hi:[1,0]
	v_pk_mul_f32 v[102:103], v[100:101], v[64:65] op_sel_hi:[1,0]
	v_cvt_pk_bf16_f32 v100, v104, v105
	v_cvt_pk_bf16_f32 v101, v106, v107
	v_cvt_pk_bf16_f32 v102, v102, v103
	v_cvt_pk_bf16_f32 v103, v108, v109
	global_store_dwordx4 v[112:113], v[100:103], off offset:256
	v_mov_b32_e32 v64, 1.0
	s_and_b64 vcc, exec, s[28:29]
	v_or_b32_e32 v102, 32, v132
	v_ashrrev_i32_e32 v103, 31, v102
	v_mov_b32_e32 v100, 1.0
	s_cbranch_vccnz .LBB0_514
	v_lshlrev_b64 v[100:101], 6, v[102:103]
	v_lshl_add_u64 v[100:101], v[174:175], 0, v[100:101]
	v_mov_b32_e32 v104, v192
	v_mov_b32_e32 v105, v193
	v_mov_b32_e32 v106, v194
	v_mov_b32_e32 v107, v195
	v_mov_b32_e32 v100, v105
	v_mov_b32_e32 v101, v106
	v_mov_b32_e32 v105, v107
	v_pk_add_f32 v[100:101], v[100:101], v[104:105]
	s_nop 0
	v_add_f32_e32 v100, v100, v101
	ds_swizzle_b32 v101, v100 offset:swizzle(SWAP,16)
	s_waitcnt lgkmcnt(0)
	v_add_f32_e32 v100, v100, v101
	v_mov_b32_e32 v101, v100
	s_nop 1
	v_permlane32_swap_b32_e32 v100, v101
	v_add_f32_e32 v100, v100, v101
	v_fmamk_f32 v100, v100, 0x3a800000, v156
	v_mul_f32_e32 v101, 0x4b800000, v100
	v_cmp_gt_f32_e32 vcc, s90, v100
	s_nop 1
	v_cndmask_b32_e32 v100, v100, v101, vcc
	v_rsq_f32_e32 v100, v100
	s_nop 0
	v_mul_f32_e32 v101, 0x45800000, v100
	v_cndmask_b32_e32 v100, v100, v101, vcc
.LBB0_514:
	v_mad_u64_u32 v[104:105], s[16:17], v102, s11, 0
	v_mov_b32_e32 v102, v105
	v_mad_u64_u32 v[102:103], s[16:17], v103, s11, v[102:103]
	v_mov_b32_e32 v105, v102
	v_lshl_add_u64 v[102:103], v[104:105], 1, s[6:7]
	v_pk_mul_f32 v[98:99], v[98:99], v[100:101] op_sel_hi:[1,0]
	v_pk_mul_f32 v[96:97], v[96:97], v[100:101] op_sel_hi:[1,0]
	v_pk_mul_f32 v[104:105], v[94:95], v[100:101] op_sel_hi:[1,0]
	v_pk_mul_f32 v[94:95], v[92:93], v[100:101] op_sel_hi:[1,0]
	v_cvt_pk_bf16_f32 v92, v96, v97
	v_cvt_pk_bf16_f32 v93, v98, v99
	v_cvt_pk_bf16_f32 v94, v94, v95
	v_cvt_pk_bf16_f32 v95, v104, v105
	v_lshl_add_u64 v[96:97], v[66:67], 1, v[102:103]
	global_store_dwordx4 v[96:97], v[92:95], off
	v_pk_mul_f32 v[90:91], v[90:91], v[100:101] op_sel_hi:[1,0]
	v_pk_mul_f32 v[88:89], v[88:89], v[100:101] op_sel_hi:[1,0]
	v_pk_mul_f32 v[92:93], v[86:87], v[100:101] op_sel_hi:[1,0]
	v_pk_mul_f32 v[86:87], v[84:85], v[100:101] op_sel_hi:[1,0]
	v_cvt_pk_bf16_f32 v84, v88, v89
	v_cvt_pk_bf16_f32 v85, v90, v91
	v_cvt_pk_bf16_f32 v86, v86, v87
	v_cvt_pk_bf16_f32 v87, v92, v93
	global_store_dwordx4 v[96:97], v[84:87], off offset:256
	s_and_b64 vcc, exec, s[28:29]
	s_nop 0
	v_or_b32_e32 v84, 48, v132
	v_ashrrev_i32_e32 v85, 31, v84
	s_cbranch_vccnz .LBB0_516
	v_lshlrev_b64 v[86:87], 6, v[84:85]
	v_lshl_add_u64 v[86:87], v[174:175], 0, v[86:87]
	v_mov_b32_e32 v86, v196
	v_mov_b32_e32 v87, v197
	v_mov_b32_e32 v88, v198
	v_mov_b32_e32 v89, v199
	v_mov_b32_e32 v90, v87
	v_mov_b32_e32 v91, v88
	v_mov_b32_e32 v87, v89
	v_pk_add_f32 v[86:87], v[90:91], v[86:87]
	s_nop 0
	v_add_f32_e32 v64, v86, v87
	ds_swizzle_b32 v86, v64 offset:swizzle(SWAP,16)
	s_waitcnt lgkmcnt(0)
	v_add_f32_e32 v64, v64, v86
	v_mov_b32_e32 v86, v64
	s_nop 1
	v_permlane32_swap_b32_e32 v64, v86
	v_add_f32_e32 v64, v64, v86
	v_fmamk_f32 v64, v64, 0x3a800000, v156
	v_mul_f32_e32 v86, 0x4b800000, v64
	v_cmp_gt_f32_e32 vcc, s90, v64
	s_nop 1
	v_cndmask_b32_e32 v64, v64, v86, vcc
	v_rsq_f32_e32 v64, v64
	s_nop 0
	v_mul_f32_e32 v86, 0x45800000, v64
	v_cndmask_b32_e32 v64, v64, v86, vcc
.LBB0_516:
	v_mad_u64_u32 v[86:87], s[16:17], v84, s11, 0
	v_mov_b32_e32 v84, v87
	v_mad_u64_u32 v[84:85], s[16:17], v85, s11, v[84:85]
	v_mov_b32_e32 v87, v84
	v_lshl_add_u64 v[84:85], v[86:87], 1, s[6:7]
	v_pk_mul_f32 v[82:83], v[82:83], v[64:65] op_sel_hi:[1,0]
	v_pk_mul_f32 v[80:81], v[80:81], v[64:65] op_sel_hi:[1,0]
	v_pk_mul_f32 v[86:87], v[78:79], v[64:65] op_sel_hi:[1,0]
	v_pk_mul_f32 v[78:79], v[76:77], v[64:65] op_sel_hi:[1,0]
	v_cvt_pk_bf16_f32 v76, v80, v81
	v_cvt_pk_bf16_f32 v77, v82, v83
	v_cvt_pk_bf16_f32 v78, v78, v79
	v_cvt_pk_bf16_f32 v79, v86, v87
	v_lshl_add_u64 v[80:81], v[66:67], 1, v[84:85]
	global_store_dwordx4 v[80:81], v[76:79], off
	v_pk_mul_f32 v[74:75], v[74:75], v[64:65] op_sel_hi:[1,0]
	v_pk_mul_f32 v[72:73], v[72:73], v[64:65] op_sel_hi:[1,0]
	v_pk_mul_f32 v[76:77], v[70:71], v[64:65] op_sel_hi:[1,0]
	v_pk_mul_f32 v[70:71], v[68:69], v[64:65] op_sel_hi:[1,0]
	v_cvt_pk_bf16_f32 v68, v72, v73
	v_cvt_pk_bf16_f32 v69, v74, v75
	v_cvt_pk_bf16_f32 v70, v70, v71
	v_cvt_pk_bf16_f32 v71, v76, v77
	global_store_dwordx4 v[80:81], v[68:71], off offset:256
	v_mov_b32_e32 v64, 1.0
	s_and_b64 vcc, exec, s[28:29]
	v_add_u32_e32 v70, 0x80, v132
	v_ashrrev_i32_e32 v71, 31, v70
	v_mov_b32_e32 v68, 1.0
	s_cbranch_vccnz .LBB0_518
	v_lshlrev_b64 v[68:69], 6, v[70:71]
	v_lshl_add_u64 v[68:69], v[174:175], 0, v[68:69]
	v_mov_b32_e32 v72, v200
	v_mov_b32_e32 v73, v201
	v_mov_b32_e32 v74, v202
	v_mov_b32_e32 v75, v203
	v_mov_b32_e32 v68, v73
	v_mov_b32_e32 v69, v74
	v_mov_b32_e32 v73, v75
	v_pk_add_f32 v[68:69], v[68:69], v[72:73]
	s_nop 0
	v_add_f32_e32 v68, v68, v69
	ds_swizzle_b32 v69, v68 offset:swizzle(SWAP,16)
	s_waitcnt lgkmcnt(0)
	v_add_f32_e32 v68, v68, v69
	v_mov_b32_e32 v69, v68
	s_nop 1
	v_permlane32_swap_b32_e32 v68, v69
	v_add_f32_e32 v68, v68, v69
	v_fmamk_f32 v68, v68, 0x3a800000, v156
	v_mul_f32_e32 v69, 0x4b800000, v68
	v_cmp_gt_f32_e32 vcc, s90, v68
	s_nop 1
	v_cndmask_b32_e32 v68, v68, v69, vcc
	v_rsq_f32_e32 v68, v68
	s_nop 0
	v_mul_f32_e32 v69, 0x45800000, v68
	v_cndmask_b32_e32 v68, v68, v69, vcc
; #define GAS __attribute__((address_space(1)))
; __device__ __forceinline__ unsigned pk2(float lo, float hi) { f32x2v v = {lo, hi}; bf16x2v b = __builtin_convertvector(v, bf16x2v); return __builtin_bit_cast(unsigned, b); }
; #define GAS __attribute__((address_space(1)))
; __device__ __forceinline__ float row_rstd(const float* ss, int row, int fq) {
;     const f32x4 a = *(GAS const f32x4*)(ss + (size_t)row * 16 + 4 * fq);
;     float s = (a[0] + a[1]) + (a[2] + a[3]);
;     s += __int_as_float(__builtin_amdgcn_ds_swizzle(__float_as_int(s), (16 << 10) | 0x1f));
;     { auto rr = __builtin_amdgcn_permlane32_swap(__float_as_uint(s), __float_as_uint(s), false, false); s = __uint_as_float(rr[0]) + __uint_as_float(rr[1]); }
;     return rsqrtf(s * (1.f / 1024) + 1e-6f);
; }
;     __device__ __forceinline__ void operator()(const f32x4 (&acc)[2][2][4][2], const Unit& u, int wr, int wc, int fr, int fq) const {
;     ...
;             for (int m = 0; m < 4; ++m) { const int row = row0 + ai * HALF + m * 16; bf16_t* rp = base + (size_t)row * ld;
;                 float rs = 1.f; if (MODE == 0 && ss) rs = row_rstd(ss, row, fq);
; #pragma unroll
;                 for (int bj = 0; bj < 2; ++bj) { int c = c0 + bj * HALF;
;                     if (MODE == 1) { const int b_ = row / TT, t_ = row - b_ * TT; rp = base; c = (((b_ * 16 + (c >> 6)) * TT + t_) * 96) + (c & 63); }
;                     if (MODE == 2) { const int b_ = c / TT, t_ = c - b_ * TT; rp = base + ((size_t)((b_ * 16 + (row >> 6)) * 64 + (row & 63))) * 4160; c = t_; }
;                     const f32x4 v0 = acc[ai][bj][m][0] * rs, v1 = acc[ai][bj][m][1] * rs; u32x4 w; w.x = pk2(v0[0], v0[1]); w.y = pk2(v0[2], v0[3]); w.z = pk2(v1[0], v1[1]); w.w = pk2(v1[2], v1[3]);
;                     *(GAS u32x4*)(rp + c) = w; } }
.LBB0_518:
	v_mad_u64_u32 v[72:73], s[16:17], v70, s11, 0
	v_mov_b32_e32 v70, v73
	v_mad_u64_u32 v[70:71], s[16:17], v71, s11, v[70:71]
	v_mov_b32_e32 v73, v70
	v_lshl_add_u64 v[70:71], v[72:73], 1, s[6:7]
	v_pk_mul_f32 v[62:63], v[62:63], v[68:69] op_sel_hi:[1,0]
	v_pk_mul_f32 v[60:61], v[60:61], v[68:69] op_sel_hi:[1,0]
	v_pk_mul_f32 v[72:73], v[58:59], v[68:69] op_sel_hi:[1,0]
	v_pk_mul_f32 v[58:59], v[56:57], v[68:69] op_sel_hi:[1,0]
	v_cvt_pk_bf16_f32 v56, v60, v61
	v_cvt_pk_bf16_f32 v57, v62, v63
	v_cvt_pk_bf16_f32 v58, v58, v59
	v_cvt_pk_bf16_f32 v59, v72, v73
	v_lshl_add_u64 v[60:61], v[66:67], 1, v[70:71]
	global_store_dwordx4 v[60:61], v[56:59], off
	v_pk_mul_f32 v[54:55], v[54:55], v[68:69] op_sel_hi:[1,0]
	v_pk_mul_f32 v[52:53], v[52:53], v[68:69] op_sel_hi:[1,0]
	v_pk_mul_f32 v[56:57], v[50:51], v[68:69] op_sel_hi:[1,0]
	v_pk_mul_f32 v[50:51], v[48:49], v[68:69] op_sel_hi:[1,0]
	v_cvt_pk_bf16_f32 v48, v52, v53
	v_cvt_pk_bf16_f32 v49, v54, v55
	v_cvt_pk_bf16_f32 v50, v50, v51
	v_cvt_pk_bf16_f32 v51, v56, v57
	global_store_dwordx4 v[60:61], v[48:51], off offset:256
	s_and_b64 vcc, exec, s[28:29]
	s_nop 0
	v_add_u32_e32 v48, 0x90, v132
	v_ashrrev_i32_e32 v49, 31, v48
	s_cbranch_vccnz .LBB0_520
	v_lshlrev_b64 v[50:51], 6, v[48:49]
	v_lshl_add_u64 v[50:51], v[174:175], 0, v[50:51]
	v_mov_b32_e32 v50, v220
	v_mov_b32_e32 v51, v221
	v_mov_b32_e32 v52, v222
	v_mov_b32_e32 v53, v223
	v_mov_b32_e32 v54, v51
	v_mov_b32_e32 v55, v52
	v_mov_b32_e32 v51, v53
	v_pk_add_f32 v[50:51], v[54:55], v[50:51]
	s_nop 0
	v_add_f32_e32 v50, v50, v51
	ds_swizzle_b32 v51, v50 offset:swizzle(SWAP,16)
	s_waitcnt lgkmcnt(0)
	v_add_f32_e32 v50, v50, v51
	v_mov_b32_e32 v51, v50
	s_nop 1
	v_permlane32_swap_b32_e32 v50, v51
	v_add_f32_e32 v50, v50, v51
	v_fmamk_f32 v50, v50, 0x3a800000, v156
	v_mul_f32_e32 v51, 0x4b800000, v50
	v_cmp_gt_f32_e32 vcc, s90, v50
	s_nop 1
	v_cndmask_b32_e32 v50, v50, v51, vcc
	v_rsq_f32_e32 v50, v50
	s_nop 0
	v_mul_f32_e32 v51, 0x45800000, v50
	v_cndmask_b32_e32 v64, v50, v51, vcc
.LBB0_520:
	v_mad_u64_u32 v[50:51], s[16:17], v48, s11, 0
	v_mov_b32_e32 v48, v51
	v_mad_u64_u32 v[48:49], s[16:17], v49, s11, v[48:49]
	v_mov_b32_e32 v51, v48
	v_lshl_add_u64 v[48:49], v[50:51], 1, s[6:7]
	v_pk_mul_f32 v[46:47], v[46:47], v[64:65] op_sel_hi:[1,0]
	v_pk_mul_f32 v[44:45], v[44:45], v[64:65] op_sel_hi:[1,0]
	v_pk_mul_f32 v[50:51], v[42:43], v[64:65] op_sel_hi:[1,0]
	v_pk_mul_f32 v[42:43], v[40:41], v[64:65] op_sel_hi:[1,0]
	v_cvt_pk_bf16_f32 v40, v44, v45
	v_cvt_pk_bf16_f32 v41, v46, v47
	v_cvt_pk_bf16_f32 v42, v42, v43
	v_cvt_pk_bf16_f32 v43, v50, v51
	v_lshl_add_u64 v[44:45], v[66:67], 1, v[48:49]
	global_store_dwordx4 v[44:45], v[40:43], off
	v_pk_mul_f32 v[38:39], v[38:39], v[64:65] op_sel_hi:[1,0]
	v_pk_mul_f32 v[36:37], v[36:37], v[64:65] op_sel_hi:[1,0]
	v_pk_mul_f32 v[40:41], v[34:35], v[64:65] op_sel_hi:[1,0]
	v_pk_mul_f32 v[34:35], v[32:33], v[64:65] op_sel_hi:[1,0]
	v_cvt_pk_bf16_f32 v32, v36, v37
	v_cvt_pk_bf16_f32 v33, v38, v39
	v_cvt_pk_bf16_f32 v34, v34, v35
	v_cvt_pk_bf16_f32 v35, v40, v41
	v_add_u32_e32 v36, 0xa0, v132
	global_store_dwordx4 v[44:45], v[32:35], off offset:256
	v_ashrrev_i32_e32 v37, 31, v36
	s_and_b64 vcc, exec, s[28:29]
	v_mov_b32_e32 v32, 1.0
	v_mov_b32_e32 v34, 1.0
	s_cbranch_vccnz .LBB0_522
	v_lshlrev_b64 v[34:35], 6, v[36:37]
	v_lshl_add_u64 v[34:35], v[174:175], 0, v[34:35]
	v_mov_b32_e32 v38, v224
	v_mov_b32_e32 v39, v225
	v_mov_b32_e32 v40, v226
	v_mov_b32_e32 v41, v227
	v_mov_b32_e32 v34, v39
	v_mov_b32_e32 v35, v40
	v_mov_b32_e32 v39, v41
	v_pk_add_f32 v[34:35], v[34:35], v[38:39]
	s_nop 0
	v_add_f32_e32 v33, v34, v35
	ds_swizzle_b32 v34, v33 offset:swizzle(SWAP,16)
	s_waitcnt lgkmcnt(0)
	v_add_f32_e32 v33, v33, v34
	v_mov_b32_e32 v34, v33
	s_nop 1
	v_permlane32_swap_b32_e32 v33, v34
	v_add_f32_e32 v33, v33, v34
	v_fmamk_f32 v33, v33, 0x3a800000, v156
	v_mul_f32_e32 v34, 0x4b800000, v33
	v_cmp_gt_f32_e32 vcc, s90, v33
	s_nop 1
	v_cndmask_b32_e32 v33, v33, v34, vcc
	v_rsq_f32_e32 v33, v33
	s_nop 0
	v_mul_f32_e32 v34, 0x45800000, v33
	v_cndmask_b32_e32 v34, v33, v34, vcc
.LBB0_522:
	v_mad_u64_u32 v[38:39], s[16:17], v36, s11, 0
	v_mov_b32_e32 v36, v39
	v_mad_u64_u32 v[36:37], s[16:17], v37, s11, v[36:37]
	v_mov_b32_e32 v39, v36
	v_lshl_add_u64 v[36:37], v[38:39], 1, s[6:7]
	v_pk_mul_f32 v[30:31], v[30:31], v[34:35] op_sel_hi:[1,0]
	v_pk_mul_f32 v[28:29], v[28:29], v[34:35] op_sel_hi:[1,0]
	v_pk_mul_f32 v[38:39], v[26:27], v[34:35] op_sel_hi:[1,0]
	v_pk_mul_f32 v[26:27], v[24:25], v[34:35] op_sel_hi:[1,0]
	v_cvt_pk_bf16_f32 v24, v28, v29
	v_cvt_pk_bf16_f32 v25, v30, v31
	v_cvt_pk_bf16_f32 v26, v26, v27
	v_cvt_pk_bf16_f32 v27, v38, v39
	v_lshl_add_u64 v[28:29], v[66:67], 1, v[36:37]
	global_store_dwordx4 v[28:29], v[24:27], off
	v_pk_mul_f32 v[22:23], v[22:23], v[34:35] op_sel_hi:[1,0]
	v_pk_mul_f32 v[20:21], v[20:21], v[34:35] op_sel_hi:[1,0]
	v_pk_mul_f32 v[24:25], v[18:19], v[34:35] op_sel_hi:[1,0]
	v_pk_mul_f32 v[18:19], v[16:17], v[34:35] op_sel_hi:[1,0]
	v_cvt_pk_bf16_f32 v16, v20, v21
	v_cvt_pk_bf16_f32 v17, v22, v23
	v_cvt_pk_bf16_f32 v18, v18, v19
	v_cvt_pk_bf16_f32 v19, v24, v25
	global_store_dwordx4 v[28:29], v[16:19], off offset:256
	s_and_b64 vcc, exec, s[28:29]
	s_nop 0
	v_add_u32_e32 v16, 0xb0, v132
	v_ashrrev_i32_e32 v17, 31, v16
	s_cbranch_vccnz .LBB0_524
	v_lshlrev_b64 v[18:19], 6, v[16:17]
	v_lshl_add_u64 v[18:19], v[174:175], 0, v[18:19]
	v_mov_b32_e32 v18, v228
	v_mov_b32_e32 v19, v229
	v_mov_b32_e32 v20, v230
	v_mov_b32_e32 v21, v231
	v_mov_b32_e32 v22, v19
	v_mov_b32_e32 v23, v20
	v_mov_b32_e32 v19, v21
	v_pk_add_f32 v[18:19], v[22:23], v[18:19]
	s_nop 0
	v_add_f32_e32 v18, v18, v19
	ds_swizzle_b32 v19, v18 offset:swizzle(SWAP,16)
	s_waitcnt lgkmcnt(0)
	v_add_f32_e32 v18, v18, v19
	v_mov_b32_e32 v19, v18
	s_nop 1
	v_permlane32_swap_b32_e32 v18, v19
	v_add_f32_e32 v18, v18, v19
	v_fmamk_f32 v18, v18, 0x3a800000, v156
	v_mul_f32_e32 v19, 0x4b800000, v18
	v_cmp_gt_f32_e32 vcc, s90, v18
	s_nop 1
	v_cndmask_b32_e32 v18, v18, v19, vcc
	v_rsq_f32_e32 v18, v18
	s_nop 0
	v_mul_f32_e32 v19, 0x45800000, v18
	v_cndmask_b32_e32 v32, v18, v19, vcc
